# PW1 with R0=36864: phase 0 streams 36864 rows, phase 1 streams 12288 rows under the two-pass weight-product unit
# speedup vs baseline: 1.0018x; 1.0018x over previous
; __device__ void p0_xconv(const Args& a) {
;     f16* XH = (f16*)(a.ws + WS_XH); float* SS = (float*)(a.ws + WS_SS);
;     int tid_ = threadIdx.x; asm volatile("" : "+v"(tid_));
;     const int lane = tid_ & 63, wv = tid_ >> 6;
;     const int nwv = (int)gridDim.x * 8;
;     for (int row0 = (int)blockIdx.x * 8 + wv; row0 < MROWS; row0 += 4 * nwv) {
.Lws_x:
	v_writelane_b32 v255, s14, 10
	v_writelane_b32 v255, s15, 11
	v_writelane_b32 v255, s20, 12
	v_writelane_b32 v255, s21, 13
	v_writelane_b32 v255, s22, 14
	v_writelane_b32 v255, s23, 15
	v_mov_b32_e32 v1, v0
	s_mov_b32 s3, 0x9000
	v_ashrrev_i32_e32 v2, 6, v1
	v_lshl_add_u32 v78, s2, 2, v2
	v_add_u32_e32 v78, -4, v78
	v_cmp_gt_i32_e32 vcc, s3, v78
	s_and_saveexec_b64 s[20:21], vcc
	s_cbranch_execz .Lxc_111
	v_and_b32_e32 v1, 63, v1
	v_mov_b32_e32 v67, 0
	v_lshlrev_b32_e32 v66, 2, v1
	v_lshlrev_b32_e32 v2, 3, v1
	v_mov_b32_e32 v3, v67
	s_movk_i32 s36, 0x80
	v_lshl_add_u64 v[68:69], s[40:41], 0, v[2:3]
	v_lshl_add_u64 v[2:3], s[40:41], 0, v[66:67]
	s_mov_b64 s[4:5], 0x1f800000
	v_cmp_gt_u32_e32 vcc, 16, v1
	v_lshl_add_u64 v[70:71], v[2:3], 0, s[4:5]
	v_cmp_eq_u32_e64 s[4:5], 0, v1
	v_mbcnt_lo_u32_b32 v1, -1, 0
	v_mbcnt_hi_u32_b32 v2, -1, v1
	v_and_b32_e32 v1, 64, v2
	v_add_u32_e32 v3, 64, v1
	v_xor_b32_e32 v1, 1, v2
	v_cmp_lt_i32_e64 s[6:7], v1, v3
	v_xor_b32_e32 v4, 2, v2
	s_waitcnt lgkmcnt(0)
	s_lshl_b32 s9, s36, 3
	v_cndmask_b32_e64 v1, v2, v1, s[6:7]
	v_cmp_lt_i32_e64 s[6:7], v4, v3
	s_add_i32 s44, s9, s9
	v_lshlrev_b32_e32 v1, 2, v1
	v_cndmask_b32_e64 v4, v2, v4, s[6:7]
	v_lshlrev_b32_e32 v80, 2, v4
	v_xor_b32_e32 v4, 4, v2
	v_cmp_lt_i32_e64 s[6:7], v4, v3
	s_lshl_b32 s33, s36, 4
	s_mul_i32 s36, s36, 24
	v_cndmask_b32_e64 v4, v2, v4, s[6:7]
	v_lshlrev_b32_e32 v81, 2, v4
	v_xor_b32_e32 v4, 8, v2
	v_cmp_lt_i32_e64 s[6:7], v4, v3
	s_mov_b64 s[22:23], 0
	s_movk_i32 s37, 0x4000
	v_cndmask_b32_e64 v4, v2, v4, s[6:7]
	v_lshlrev_b32_e32 v82, 2, v4
	v_xor_b32_e32 v4, 16, v2
	v_cmp_lt_i32_e64 s[6:7], v4, v3
	v_mov_b32_e32 v85, s19
	v_mov_b32_e32 v86, s17
	v_cndmask_b32_e64 v4, v2, v4, s[6:7]
	v_lshlrev_b32_e32 v83, 2, v4
	v_xor_b32_e32 v4, 32, v2
	v_cmp_lt_i32_e64 s[6:7], v4, v3
	v_mov_b32_e32 v87, s18
	v_mov_b32_e32 v88, s16
	v_cndmask_b32_e64 v2, v2, v4, s[6:7]
	v_lshlrev_b32_e32 v84, 2, v2
	v_lshlrev_b32_e32 v66, 2, v66
	s_add_i32 s44, s44, s9
	s_mov_b32 s45, 0x8fff
	s_branch .Lxc_94

; __device__ void p0_xconv(const Args& a) {
;     ...
;     for (int row0 = (int)blockIdx.x * 8 + wv; row0 < MROWS; row0 += 4 * nwv) {
;         f32x4 v[4][4];
; #pragma unroll
;         for (int r = 0; r < 4; ++r) {
;             const int row = row0 + r * nwv;
;             if (row < MROWS) {
;                 const float* src = (row < ROWS_PROMPT) ? a.x_prompt + (size_t)row * DM : a.x_sample + (size_t)(row - ROWS_PROMPT) * DM;
; #pragma unroll
;                 for (int i = 0; i < 4; ++i) v[r][i] = __builtin_nontemporal_load((const f32x4*)(src + i * 256 + lane * 4));
;             }
;         }
; #pragma unroll
;         for (int r = 0; r < 4; ++r) {
;             const int row = row0 + r * nwv;
;             if (row < MROWS) {
;                 float ss = 0.f;
; #pragma unroll
;                 for (int i = 0; i < 4; ++i) {
;                     const f32x4 x = v[r][i];
;                     ss += (x[0] * x[0] + x[1] * x[1]) + (x[2] * x[2] + x[3] * x[3]);
;                     f16x4 h; h[0] = (f16)x[0]; h[1] = (f16)x[1]; h[2] = (f16)x[2]; h[3] = (f16)x[3];
;                     *(f16x4*)(XH + (size_t)row * DM + i * 256 + lane * 4) = h;
.Lpw_x:
	s_barrier
	v_and_b32_e32 v136, 63, v0
	v_lshrrev_b32_e32 v137, 6, v0
	s_nop 0
	v_readfirstlane_b32 s3, v137
	s_nop 3
	s_lshl_b32 s4, s2, 2
	s_add_i32 s3, s3, s4
	s_add_i32 s3, s3, -4
	s_mov_b64 s[12:13], 1
	v_xor_b32_e32 v130, 1, v136
	v_lshlrev_b32_e32 v130, 2, v130
	v_xor_b32_e32 v131, 2, v136
	v_lshlrev_b32_e32 v131, 2, v131
	v_xor_b32_e32 v132, 4, v136
	v_lshlrev_b32_e32 v132, 2, v132
	v_xor_b32_e32 v133, 8, v136
	v_lshlrev_b32_e32 v133, 2, v133
	v_xor_b32_e32 v134, 16, v136
	v_lshlrev_b32_e32 v134, 2, v134
	v_xor_b32_e32 v135, 32, v136
	v_lshlrev_b32_e32 v135, 2, v135
	v_lshlrev_b32_e32 v140, 4, v136
	v_lshlrev_b32_e32 v144, 3, v136
	v_lshlrev_b32_e32 v186, 2, v136
	v_lshlrev_b32_e32 v141, 4, v136
	v_add_u32_e32 v141, 0x400000, v141
	v_lshlrev_b32_e32 v145, 3, v136
	v_add_u32_e32 v145, 0x200000, v145
	v_lshlrev_b32_e32 v187, 2, v136
	v_add_u32_e32 v187, 0x10000, v187
	v_lshlrev_b32_e32 v142, 4, v136
	v_add_u32_e32 v142, 0x800000, v142
	v_lshlrev_b32_e32 v146, 3, v136
	v_add_u32_e32 v146, 0x400000, v146
	v_lshlrev_b32_e32 v188, 2, v136
	v_add_u32_e32 v188, 0x20000, v188
	v_lshlrev_b32_e32 v143, 4, v136
	v_add_u32_e32 v143, 0xc00000, v143
	v_lshlrev_b32_e32 v147, 3, v136
	v_add_u32_e32 v147, 0x600000, v147
	v_lshlrev_b32_e32 v189, 2, v136
	v_add_u32_e32 v189, 0x30000, v189
	s_add_i32 s6, s3, 0x5000
	s_lshl_b32 s6, s6, 12
	s_add_u32 s4, s18, s6
	s_addc_u32 s5, s19, 0
	global_load_dwordx4 v[2:5], v140, s[4:5] nt
	global_load_dwordx4 v[6:9], v140, s[4:5] offset:1024 nt
	global_load_dwordx4 v[10:13], v140, s[4:5] offset:2048 nt
	global_load_dwordx4 v[14:17], v140, s[4:5] offset:3072 nt
	global_load_dwordx4 v[18:21], v141, s[4:5] nt
	global_load_dwordx4 v[22:25], v141, s[4:5] offset:1024 nt
	global_load_dwordx4 v[26:29], v141, s[4:5] offset:2048 nt
	global_load_dwordx4 v[30:33], v141, s[4:5] offset:3072 nt
	global_load_dwordx4 v[34:37], v142, s[4:5] nt
	global_load_dwordx4 v[38:41], v142, s[4:5] offset:1024 nt
	global_load_dwordx4 v[42:45], v142, s[4:5] offset:2048 nt
	global_load_dwordx4 v[46:49], v142, s[4:5] offset:3072 nt
	global_load_dwordx4 v[50:53], v143, s[4:5] nt
	global_load_dwordx4 v[54:57], v143, s[4:5] offset:1024 nt
	global_load_dwordx4 v[58:61], v143, s[4:5] offset:2048 nt
	global_load_dwordx4 v[62:65], v143, s[4:5] offset:3072 nt
	s_add_i32 s6, s3, 0x6000
	s_lshl_b32 s6, s6, 12
	s_add_u32 s4, s18, s6
	s_addc_u32 s5, s19, 0
	global_load_dwordx4 v[66:69], v140, s[4:5] nt
	global_load_dwordx4 v[70:73], v140, s[4:5] offset:1024 nt
	global_load_dwordx4 v[74:77], v140, s[4:5] offset:2048 nt
	global_load_dwordx4 v[78:81], v140, s[4:5] offset:3072 nt
	global_load_dwordx4 v[82:85], v141, s[4:5] nt
	global_load_dwordx4 v[86:89], v141, s[4:5] offset:1024 nt
	global_load_dwordx4 v[90:93], v141, s[4:5] offset:2048 nt
	global_load_dwordx4 v[94:97], v141, s[4:5] offset:3072 nt
	global_load_dwordx4 v[98:101], v142, s[4:5] nt
	global_load_dwordx4 v[102:105], v142, s[4:5] offset:1024 nt
	global_load_dwordx4 v[106:109], v142, s[4:5] offset:2048 nt
	global_load_dwordx4 v[110:113], v142, s[4:5] offset:3072 nt
	global_load_dwordx4 v[114:117], v143, s[4:5] nt
	global_load_dwordx4 v[118:121], v143, s[4:5] offset:1024 nt
	global_load_dwordx4 v[122:125], v143, s[4:5] offset:2048 nt
	global_load_dwordx4 v[126:129], v143, s[4:5] offset:3072 nt
	s_waitcnt vmcnt(16)
	s_add_i32 s6, s3, 0x9000
	s_lshl_b32 s7, s6, 11
	s_add_u32 s10, s40, s7
	s_addc_u32 s11, s41, 0
	s_lshl_b32 s7, s6, 6
	s_add_u32 s6, s40, s7
	s_addc_u32 s7, s41, 0
	s_add_u32 s6, s6, 0x1f800000
	s_addc_u32 s7, s7, 0
	v_mul_f32_e32 v150, v3, v3
	v_mul_f32_e32 v151, v5, v5
	v_fmac_f32_e32 v150, v2, v2
	v_fmac_f32_e32 v151, v4, v4
	v_add_f32_e32 v160, v150, v151
	v_cvt_pk_f16_f32 v170, v2, v3
	v_cvt_pk_f16_f32 v171, v4, v5
	v_mul_f32_e32 v150, v7, v7
	v_mul_f32_e32 v151, v9, v9
	v_fmac_f32_e32 v150, v6, v6
	v_fmac_f32_e32 v151, v8, v8
	v_add_f32_e32 v152, v150, v151
	v_add_f32_e32 v160, v160, v152
	v_cvt_pk_f16_f32 v172, v6, v7
	v_cvt_pk_f16_f32 v173, v8, v9
	v_mul_f32_e32 v150, v11, v11
	v_mul_f32_e32 v151, v13, v13
	v_fmac_f32_e32 v150, v10, v10
	v_fmac_f32_e32 v151, v12, v12
	v_add_f32_e32 v152, v150, v151
	v_add_f32_e32 v160, v160, v152
	v_cvt_pk_f16_f32 v174, v10, v11
	v_cvt_pk_f16_f32 v175, v12, v13
	v_mul_f32_e32 v150, v15, v15
	v_mul_f32_e32 v151, v17, v17
	v_fmac_f32_e32 v150, v14, v14
	v_fmac_f32_e32 v151, v16, v16
	v_add_f32_e32 v152, v150, v151
	v_add_f32_e32 v160, v160, v152
	v_cvt_pk_f16_f32 v176, v14, v15
	v_cvt_pk_f16_f32 v177, v16, v17
	global_store_dwordx2 v144, v[170:171], s[10:11]
	global_store_dwordx2 v144, v[172:173], s[10:11] offset:512
	global_store_dwordx2 v144, v[174:175], s[10:11] offset:1024
	global_store_dwordx2 v144, v[176:177], s[10:11] offset:1536
	v_mul_f32_e32 v150, v19, v19
	v_mul_f32_e32 v151, v21, v21
	v_fmac_f32_e32 v150, v18, v18
	v_fmac_f32_e32 v151, v20, v20
	v_add_f32_e32 v161, v150, v151
	v_cvt_pk_f16_f32 v178, v18, v19
	v_cvt_pk_f16_f32 v179, v20, v21
	v_mul_f32_e32 v150, v23, v23
	v_mul_f32_e32 v151, v25, v25
	v_fmac_f32_e32 v150, v22, v22
	v_fmac_f32_e32 v151, v24, v24
	v_add_f32_e32 v152, v150, v151
	v_add_f32_e32 v161, v161, v152
	v_cvt_pk_f16_f32 v180, v22, v23
	v_cvt_pk_f16_f32 v181, v24, v25
	v_mul_f32_e32 v150, v27, v27
	v_mul_f32_e32 v151, v29, v29
	v_fmac_f32_e32 v150, v26, v26
	v_fmac_f32_e32 v151, v28, v28
	v_add_f32_e32 v152, v150, v151
	v_add_f32_e32 v161, v161, v152
	v_cvt_pk_f16_f32 v182, v26, v27
	v_cvt_pk_f16_f32 v183, v28, v29
	v_mul_f32_e32 v150, v31, v31
	v_mul_f32_e32 v151, v33, v33
	v_fmac_f32_e32 v150, v30, v30
	v_fmac_f32_e32 v151, v32, v32
	v_add_f32_e32 v152, v150, v151
	v_add_f32_e32 v161, v161, v152
; __device__ void p0_xconv(const Args& a) {
;     ...
;                 float ss = 0.f;
; #pragma unroll
;                 for (int i = 0; i < 4; ++i) {
;                     const f32x4 x = v[r][i];
;                     ss += (x[0] * x[0] + x[1] * x[1]) + (x[2] * x[2] + x[3] * x[3]);
;                     f16x4 h; h[0] = (f16)x[0]; h[1] = (f16)x[1]; h[2] = (f16)x[2]; h[3] = (f16)x[3];
;                     *(f16x4*)(XH + (size_t)row * DM + i * 256 + lane * 4) = h;
;                 }
; #pragma unroll
;                 for (int o = 1; o < 64; o <<= 1) ss += __shfl_xor(ss, o);
;                 if (lane < 16) SS[(size_t)row * 16 + lane] = (lane == 0) ? ss : 0.f;
	v_cvt_pk_f16_f32 v184, v30, v31
	v_cvt_pk_f16_f32 v185, v32, v33
	global_store_dwordx2 v145, v[178:179], s[10:11]
	global_store_dwordx2 v145, v[180:181], s[10:11] offset:512
	global_store_dwordx2 v145, v[182:183], s[10:11] offset:1024
	global_store_dwordx2 v145, v[184:185], s[10:11] offset:1536
	v_mul_f32_e32 v150, v35, v35
	v_mul_f32_e32 v151, v37, v37
	v_fmac_f32_e32 v150, v34, v34
	v_fmac_f32_e32 v151, v36, v36
	v_add_f32_e32 v162, v150, v151
	v_cvt_pk_f16_f32 v170, v34, v35
	v_cvt_pk_f16_f32 v171, v36, v37
	v_mul_f32_e32 v150, v39, v39
	v_mul_f32_e32 v151, v41, v41
	v_fmac_f32_e32 v150, v38, v38
	v_fmac_f32_e32 v151, v40, v40
	v_add_f32_e32 v152, v150, v151
	v_add_f32_e32 v162, v162, v152
	v_cvt_pk_f16_f32 v172, v38, v39
	v_cvt_pk_f16_f32 v173, v40, v41
	v_mul_f32_e32 v150, v43, v43
	v_mul_f32_e32 v151, v45, v45
	v_fmac_f32_e32 v150, v42, v42
	v_fmac_f32_e32 v151, v44, v44
	v_add_f32_e32 v152, v150, v151
	v_add_f32_e32 v162, v162, v152
	v_cvt_pk_f16_f32 v174, v42, v43
	v_cvt_pk_f16_f32 v175, v44, v45
	v_mul_f32_e32 v150, v47, v47
	v_mul_f32_e32 v151, v49, v49
	v_fmac_f32_e32 v150, v46, v46
	v_fmac_f32_e32 v151, v48, v48
	v_add_f32_e32 v152, v150, v151
	v_add_f32_e32 v162, v162, v152
	v_cvt_pk_f16_f32 v176, v46, v47
	v_cvt_pk_f16_f32 v177, v48, v49
	global_store_dwordx2 v146, v[170:171], s[10:11]
	global_store_dwordx2 v146, v[172:173], s[10:11] offset:512
	global_store_dwordx2 v146, v[174:175], s[10:11] offset:1024
	global_store_dwordx2 v146, v[176:177], s[10:11] offset:1536
	v_mul_f32_e32 v150, v51, v51
	v_mul_f32_e32 v151, v53, v53
	v_fmac_f32_e32 v150, v50, v50
	v_fmac_f32_e32 v151, v52, v52
	v_add_f32_e32 v163, v150, v151
	v_cvt_pk_f16_f32 v178, v50, v51
	v_cvt_pk_f16_f32 v179, v52, v53
	v_mul_f32_e32 v150, v55, v55
	v_mul_f32_e32 v151, v57, v57
	v_fmac_f32_e32 v150, v54, v54
	v_fmac_f32_e32 v151, v56, v56
	v_add_f32_e32 v152, v150, v151
	v_add_f32_e32 v163, v163, v152
	v_cvt_pk_f16_f32 v180, v54, v55
	v_cvt_pk_f16_f32 v181, v56, v57
	v_mul_f32_e32 v150, v59, v59
	v_mul_f32_e32 v151, v61, v61
	v_fmac_f32_e32 v150, v58, v58
	v_fmac_f32_e32 v151, v60, v60
	v_add_f32_e32 v152, v150, v151
	v_add_f32_e32 v163, v163, v152
	v_cvt_pk_f16_f32 v182, v58, v59
	v_cvt_pk_f16_f32 v183, v60, v61
	v_mul_f32_e32 v150, v63, v63
	v_mul_f32_e32 v151, v65, v65
	v_fmac_f32_e32 v150, v62, v62
	v_fmac_f32_e32 v151, v64, v64
	v_add_f32_e32 v152, v150, v151
	v_add_f32_e32 v163, v163, v152
	v_cvt_pk_f16_f32 v184, v62, v63
	v_cvt_pk_f16_f32 v185, v64, v65
	global_store_dwordx2 v147, v[178:179], s[10:11]
	global_store_dwordx2 v147, v[180:181], s[10:11] offset:512
	global_store_dwordx2 v147, v[182:183], s[10:11] offset:1024
	global_store_dwordx2 v147, v[184:185], s[10:11] offset:1536
	ds_bpermute_b32 v164, v130, v160
	ds_bpermute_b32 v165, v130, v161
	ds_bpermute_b32 v166, v130, v162
	ds_bpermute_b32 v167, v130, v163
	s_waitcnt lgkmcnt(0)
	v_add_f32_e32 v160, v160, v164
	v_add_f32_e32 v161, v161, v165
	v_add_f32_e32 v162, v162, v166
	v_add_f32_e32 v163, v163, v167
	ds_bpermute_b32 v164, v131, v160
	ds_bpermute_b32 v165, v131, v161
	ds_bpermute_b32 v166, v131, v162
	ds_bpermute_b32 v167, v131, v163
	s_waitcnt lgkmcnt(0)
	v_add_f32_e32 v160, v160, v164
	v_add_f32_e32 v161, v161, v165
	v_add_f32_e32 v162, v162, v166
	v_add_f32_e32 v163, v163, v167
	ds_bpermute_b32 v164, v132, v160
	ds_bpermute_b32 v165, v132, v161
	ds_bpermute_b32 v166, v132, v162
	ds_bpermute_b32 v167, v132, v163
	s_waitcnt lgkmcnt(0)
	v_add_f32_e32 v160, v160, v164
	v_add_f32_e32 v161, v161, v165
	v_add_f32_e32 v162, v162, v166
	v_add_f32_e32 v163, v163, v167
	ds_bpermute_b32 v164, v133, v160
	ds_bpermute_b32 v165, v133, v161
	ds_bpermute_b32 v166, v133, v162
	ds_bpermute_b32 v167, v133, v163
	s_waitcnt lgkmcnt(0)
	v_add_f32_e32 v160, v160, v164
	v_add_f32_e32 v161, v161, v165
	v_add_f32_e32 v162, v162, v166
	v_add_f32_e32 v163, v163, v167
	ds_bpermute_b32 v164, v134, v160
	ds_bpermute_b32 v165, v134, v161
	ds_bpermute_b32 v166, v134, v162
	ds_bpermute_b32 v167, v134, v163
	s_waitcnt lgkmcnt(0)
	v_add_f32_e32 v160, v160, v164
	v_add_f32_e32 v161, v161, v165
	v_add_f32_e32 v162, v162, v166
	v_add_f32_e32 v163, v163, v167
	ds_bpermute_b32 v164, v135, v160
	ds_bpermute_b32 v165, v135, v161
	ds_bpermute_b32 v166, v135, v162
	ds_bpermute_b32 v167, v135, v163
	s_waitcnt lgkmcnt(0)
	v_add_f32_e32 v160, v160, v164
	v_add_f32_e32 v161, v161, v165
	v_add_f32_e32 v162, v162, v166
	v_add_f32_e32 v163, v163, v167
	v_cndmask_b32_e64 v164, 0, v160, s[12:13]
	v_cndmask_b32_e64 v165, 0, v161, s[12:13]
	v_cndmask_b32_e64 v166, 0, v162, s[12:13]
	v_cndmask_b32_e64 v167, 0, v163, s[12:13]
	s_mov_b64 exec, 0xffff
	global_store_dword v186, v164, s[6:7]
	global_store_dword v187, v165, s[6:7]
	global_store_dword v188, v166, s[6:7]
	global_store_dword v189, v167, s[6:7]
	s_mov_b64 exec, -1
	s_barrier
; __device__ void p0_xconv(const Args& a) {
;     ...
;     for (int row0 = (int)blockIdx.x * 8 + wv; row0 < MROWS; row0 += 4 * nwv) {
;         f32x4 v[4][4];
; #pragma unroll
;         for (int r = 0; r < 4; ++r) {
;             const int row = row0 + r * nwv;
;             if (row < MROWS) {
;                 const float* src = (row < ROWS_PROMPT) ? a.x_prompt + (size_t)row * DM : a.x_sample + (size_t)(row - ROWS_PROMPT) * DM;
; #pragma unroll
;                 for (int i = 0; i < 4; ++i) v[r][i] = __builtin_nontemporal_load((const f32x4*)(src + i * 256 + lane * 4));
;             }
;         }
; #pragma unroll
;         for (int r = 0; r < 4; ++r) {
;             const int row = row0 + r * nwv;
;             if (row < MROWS) {
;                 float ss = 0.f;
; #pragma unroll
;                 for (int i = 0; i < 4; ++i) {
;                     const f32x4 x = v[r][i];
;                     ss += (x[0] * x[0] + x[1] * x[1]) + (x[2] * x[2] + x[3] * x[3]);
;                     f16x4 h; h[0] = (f16)x[0]; h[1] = (f16)x[1]; h[2] = (f16)x[2]; h[3] = (f16)x[3];
;                     *(f16x4*)(XH + (size_t)row * DM + i * 256 + lane * 4) = h;
	s_add_i32 s6, s3, 0x7000
	s_lshl_b32 s6, s6, 12
	s_add_u32 s4, s18, s6
	s_addc_u32 s5, s19, 0
	global_load_dwordx4 v[2:5], v140, s[4:5] nt
	global_load_dwordx4 v[6:9], v140, s[4:5] offset:1024 nt
	global_load_dwordx4 v[10:13], v140, s[4:5] offset:2048 nt
	global_load_dwordx4 v[14:17], v140, s[4:5] offset:3072 nt
	global_load_dwordx4 v[18:21], v141, s[4:5] nt
	global_load_dwordx4 v[22:25], v141, s[4:5] offset:1024 nt
	global_load_dwordx4 v[26:29], v141, s[4:5] offset:2048 nt
	global_load_dwordx4 v[30:33], v141, s[4:5] offset:3072 nt
	global_load_dwordx4 v[34:37], v142, s[4:5] nt
	global_load_dwordx4 v[38:41], v142, s[4:5] offset:1024 nt
	global_load_dwordx4 v[42:45], v142, s[4:5] offset:2048 nt
	global_load_dwordx4 v[46:49], v142, s[4:5] offset:3072 nt
	global_load_dwordx4 v[50:53], v143, s[4:5] nt
	global_load_dwordx4 v[54:57], v143, s[4:5] offset:1024 nt
	global_load_dwordx4 v[58:61], v143, s[4:5] offset:2048 nt
	global_load_dwordx4 v[62:65], v143, s[4:5] offset:3072 nt
	s_waitcnt vmcnt(36)
	s_add_i32 s6, s3, 0xa000
	s_lshl_b32 s7, s6, 11
	s_add_u32 s10, s40, s7
	s_addc_u32 s11, s41, 0
	s_lshl_b32 s7, s6, 6
	s_add_u32 s6, s40, s7
	s_addc_u32 s7, s41, 0
	s_add_u32 s6, s6, 0x1f800000
	s_addc_u32 s7, s7, 0
	v_mul_f32_e32 v150, v67, v67
	v_mul_f32_e32 v151, v69, v69
	v_fmac_f32_e32 v150, v66, v66
	v_fmac_f32_e32 v151, v68, v68
	v_add_f32_e32 v160, v150, v151
	v_cvt_pk_f16_f32 v170, v66, v67
	v_cvt_pk_f16_f32 v171, v68, v69
	v_mul_f32_e32 v150, v71, v71
	v_mul_f32_e32 v151, v73, v73
	v_fmac_f32_e32 v150, v70, v70
	v_fmac_f32_e32 v151, v72, v72
	v_add_f32_e32 v152, v150, v151
	v_add_f32_e32 v160, v160, v152
	v_cvt_pk_f16_f32 v172, v70, v71
	v_cvt_pk_f16_f32 v173, v72, v73
	v_mul_f32_e32 v150, v75, v75
	v_mul_f32_e32 v151, v77, v77
	v_fmac_f32_e32 v150, v74, v74
	v_fmac_f32_e32 v151, v76, v76
	v_add_f32_e32 v152, v150, v151
	v_add_f32_e32 v160, v160, v152
	v_cvt_pk_f16_f32 v174, v74, v75
	v_cvt_pk_f16_f32 v175, v76, v77
	v_mul_f32_e32 v150, v79, v79
	v_mul_f32_e32 v151, v81, v81
	v_fmac_f32_e32 v150, v78, v78
	v_fmac_f32_e32 v151, v80, v80
	v_add_f32_e32 v152, v150, v151
	v_add_f32_e32 v160, v160, v152
	v_cvt_pk_f16_f32 v176, v78, v79
	v_cvt_pk_f16_f32 v177, v80, v81
	global_store_dwordx2 v144, v[170:171], s[10:11]
	global_store_dwordx2 v144, v[172:173], s[10:11] offset:512
	global_store_dwordx2 v144, v[174:175], s[10:11] offset:1024
	global_store_dwordx2 v144, v[176:177], s[10:11] offset:1536
	v_mul_f32_e32 v150, v83, v83
	v_mul_f32_e32 v151, v85, v85
	v_fmac_f32_e32 v150, v82, v82
	v_fmac_f32_e32 v151, v84, v84
	v_add_f32_e32 v161, v150, v151
	v_cvt_pk_f16_f32 v178, v82, v83
	v_cvt_pk_f16_f32 v179, v84, v85
	v_mul_f32_e32 v150, v87, v87
	v_mul_f32_e32 v151, v89, v89
	v_fmac_f32_e32 v150, v86, v86
	v_fmac_f32_e32 v151, v88, v88
	v_add_f32_e32 v152, v150, v151
	v_add_f32_e32 v161, v161, v152
	v_cvt_pk_f16_f32 v180, v86, v87
	v_cvt_pk_f16_f32 v181, v88, v89
	v_mul_f32_e32 v150, v91, v91
	v_mul_f32_e32 v151, v93, v93
	v_fmac_f32_e32 v150, v90, v90
	v_fmac_f32_e32 v151, v92, v92
	v_add_f32_e32 v152, v150, v151
	v_add_f32_e32 v161, v161, v152
	v_cvt_pk_f16_f32 v182, v90, v91
	v_cvt_pk_f16_f32 v183, v92, v93
	v_mul_f32_e32 v150, v95, v95
	v_mul_f32_e32 v151, v97, v97
	v_fmac_f32_e32 v150, v94, v94
	v_fmac_f32_e32 v151, v96, v96
	v_add_f32_e32 v152, v150, v151
	v_add_f32_e32 v161, v161, v152
	v_cvt_pk_f16_f32 v184, v94, v95
	v_cvt_pk_f16_f32 v185, v96, v97
	global_store_dwordx2 v145, v[178:179], s[10:11]
	global_store_dwordx2 v145, v[180:181], s[10:11] offset:512
	global_store_dwordx2 v145, v[182:183], s[10:11] offset:1024
	global_store_dwordx2 v145, v[184:185], s[10:11] offset:1536
	v_mul_f32_e32 v150, v99, v99
	v_mul_f32_e32 v151, v101, v101
	v_fmac_f32_e32 v150, v98, v98
	v_fmac_f32_e32 v151, v100, v100
	v_add_f32_e32 v162, v150, v151
	v_cvt_pk_f16_f32 v170, v98, v99
	v_cvt_pk_f16_f32 v171, v100, v101
	v_mul_f32_e32 v150, v103, v103
	v_mul_f32_e32 v151, v105, v105
	v_fmac_f32_e32 v150, v102, v102
	v_fmac_f32_e32 v151, v104, v104
	v_add_f32_e32 v152, v150, v151
	v_add_f32_e32 v162, v162, v152
	v_cvt_pk_f16_f32 v172, v102, v103
	v_cvt_pk_f16_f32 v173, v104, v105
	v_mul_f32_e32 v150, v107, v107
	v_mul_f32_e32 v151, v109, v109
	v_fmac_f32_e32 v150, v106, v106
	v_fmac_f32_e32 v151, v108, v108
	v_add_f32_e32 v152, v150, v151
	v_add_f32_e32 v162, v162, v152
	v_cvt_pk_f16_f32 v174, v106, v107
	v_cvt_pk_f16_f32 v175, v108, v109
	v_mul_f32_e32 v150, v111, v111
	v_mul_f32_e32 v151, v113, v113
	v_fmac_f32_e32 v150, v110, v110
	v_fmac_f32_e32 v151, v112, v112
	v_add_f32_e32 v152, v150, v151
	v_add_f32_e32 v162, v162, v152
	v_cvt_pk_f16_f32 v176, v110, v111
	v_cvt_pk_f16_f32 v177, v112, v113
	global_store_dwordx2 v146, v[170:171], s[10:11]
	global_store_dwordx2 v146, v[172:173], s[10:11] offset:512
	global_store_dwordx2 v146, v[174:175], s[10:11] offset:1024
	global_store_dwordx2 v146, v[176:177], s[10:11] offset:1536
	v_mul_f32_e32 v150, v115, v115
	v_mul_f32_e32 v151, v117, v117
	v_fmac_f32_e32 v150, v114, v114
	v_fmac_f32_e32 v151, v116, v116
	v_add_f32_e32 v163, v150, v151
	v_cvt_pk_f16_f32 v178, v114, v115
	v_cvt_pk_f16_f32 v179, v116, v117
	v_mul_f32_e32 v150, v119, v119
	v_mul_f32_e32 v151, v121, v121
	v_fmac_f32_e32 v150, v118, v118
	v_fmac_f32_e32 v151, v120, v120
	v_add_f32_e32 v152, v150, v151
	v_add_f32_e32 v163, v163, v152
	v_cvt_pk_f16_f32 v180, v118, v119
	v_cvt_pk_f16_f32 v181, v120, v121
	v_mul_f32_e32 v150, v123, v123
	v_mul_f32_e32 v151, v125, v125
	v_fmac_f32_e32 v150, v122, v122
	v_fmac_f32_e32 v151, v124, v124
	v_add_f32_e32 v152, v150, v151
	v_add_f32_e32 v163, v163, v152
	v_cvt_pk_f16_f32 v182, v122, v123
	v_cvt_pk_f16_f32 v183, v124, v125
	v_mul_f32_e32 v150, v127, v127
	v_mul_f32_e32 v151, v129, v129
	v_fmac_f32_e32 v150, v126, v126
	v_fmac_f32_e32 v151, v128, v128
	v_add_f32_e32 v152, v150, v151
	v_add_f32_e32 v163, v163, v152
	v_cvt_pk_f16_f32 v184, v126, v127
	v_cvt_pk_f16_f32 v185, v128, v129
	global_store_dwordx2 v147, v[178:179], s[10:11]
	global_store_dwordx2 v147, v[180:181], s[10:11] offset:512
	global_store_dwordx2 v147, v[182:183], s[10:11] offset:1024
	global_store_dwordx2 v147, v[184:185], s[10:11] offset:1536
	ds_bpermute_b32 v164, v130, v160
	ds_bpermute_b32 v165, v130, v161
	ds_bpermute_b32 v166, v130, v162
	ds_bpermute_b32 v167, v130, v163
	s_waitcnt lgkmcnt(0)
; __device__ void p0_xconv(const Args& a) {
;     ...
;                 float ss = 0.f;
; #pragma unroll
;                 for (int i = 0; i < 4; ++i) {
;                     const f32x4 x = v[r][i];
;                     ss += (x[0] * x[0] + x[1] * x[1]) + (x[2] * x[2] + x[3] * x[3]);
;                     f16x4 h; h[0] = (f16)x[0]; h[1] = (f16)x[1]; h[2] = (f16)x[2]; h[3] = (f16)x[3];
;                     *(f16x4*)(XH + (size_t)row * DM + i * 256 + lane * 4) = h;
;                 }
; #pragma unroll
;                 for (int o = 1; o < 64; o <<= 1) ss += __shfl_xor(ss, o);
;                 if (lane < 16) SS[(size_t)row * 16 + lane] = (lane == 0) ? ss : 0.f;
	v_add_f32_e32 v160, v160, v164
	v_add_f32_e32 v161, v161, v165
	v_add_f32_e32 v162, v162, v166
	v_add_f32_e32 v163, v163, v167
	ds_bpermute_b32 v164, v131, v160
	ds_bpermute_b32 v165, v131, v161
	ds_bpermute_b32 v166, v131, v162
	ds_bpermute_b32 v167, v131, v163
	s_waitcnt lgkmcnt(0)
	v_add_f32_e32 v160, v160, v164
	v_add_f32_e32 v161, v161, v165
	v_add_f32_e32 v162, v162, v166
	v_add_f32_e32 v163, v163, v167
	ds_bpermute_b32 v164, v132, v160
	ds_bpermute_b32 v165, v132, v161
	ds_bpermute_b32 v166, v132, v162
	ds_bpermute_b32 v167, v132, v163
	s_waitcnt lgkmcnt(0)
	v_add_f32_e32 v160, v160, v164
	v_add_f32_e32 v161, v161, v165
	v_add_f32_e32 v162, v162, v166
	v_add_f32_e32 v163, v163, v167
	ds_bpermute_b32 v164, v133, v160
	ds_bpermute_b32 v165, v133, v161
	ds_bpermute_b32 v166, v133, v162
	ds_bpermute_b32 v167, v133, v163
	s_waitcnt lgkmcnt(0)
	v_add_f32_e32 v160, v160, v164
	v_add_f32_e32 v161, v161, v165
	v_add_f32_e32 v162, v162, v166
	v_add_f32_e32 v163, v163, v167
	ds_bpermute_b32 v164, v134, v160
	ds_bpermute_b32 v165, v134, v161
	ds_bpermute_b32 v166, v134, v162
	ds_bpermute_b32 v167, v134, v163
	s_waitcnt lgkmcnt(0)
	v_add_f32_e32 v160, v160, v164
	v_add_f32_e32 v161, v161, v165
	v_add_f32_e32 v162, v162, v166
	v_add_f32_e32 v163, v163, v167
	ds_bpermute_b32 v164, v135, v160
	ds_bpermute_b32 v165, v135, v161
	ds_bpermute_b32 v166, v135, v162
	ds_bpermute_b32 v167, v135, v163
	s_waitcnt lgkmcnt(0)
	v_add_f32_e32 v160, v160, v164
	v_add_f32_e32 v161, v161, v165
	v_add_f32_e32 v162, v162, v166
	v_add_f32_e32 v163, v163, v167
	v_cndmask_b32_e64 v164, 0, v160, s[12:13]
	v_cndmask_b32_e64 v165, 0, v161, s[12:13]
	v_cndmask_b32_e64 v166, 0, v162, s[12:13]
	v_cndmask_b32_e64 v167, 0, v163, s[12:13]
	s_mov_b64 exec, 0xffff
	global_store_dword v186, v164, s[6:7]
	global_store_dword v187, v165, s[6:7]
	global_store_dword v188, v166, s[6:7]
	global_store_dword v189, v167, s[6:7]
	s_mov_b64 exec, -1
	s_waitcnt vmcnt(20)
	s_add_i32 s6, s3, 0xb000
	s_lshl_b32 s7, s6, 11
	s_add_u32 s10, s40, s7
	s_addc_u32 s11, s41, 0
	s_lshl_b32 s7, s6, 6
	s_add_u32 s6, s40, s7
	s_addc_u32 s7, s41, 0
	s_add_u32 s6, s6, 0x1f800000
	s_addc_u32 s7, s7, 0
	v_mul_f32_e32 v150, v3, v3
	v_mul_f32_e32 v151, v5, v5
	v_fmac_f32_e32 v150, v2, v2
	v_fmac_f32_e32 v151, v4, v4
	v_add_f32_e32 v160, v150, v151
	v_cvt_pk_f16_f32 v170, v2, v3
	v_cvt_pk_f16_f32 v171, v4, v5
	v_mul_f32_e32 v150, v7, v7
	v_mul_f32_e32 v151, v9, v9
	v_fmac_f32_e32 v150, v6, v6
	v_fmac_f32_e32 v151, v8, v8
	v_add_f32_e32 v152, v150, v151
	v_add_f32_e32 v160, v160, v152
	v_cvt_pk_f16_f32 v172, v6, v7
	v_cvt_pk_f16_f32 v173, v8, v9
	v_mul_f32_e32 v150, v11, v11
	v_mul_f32_e32 v151, v13, v13
	v_fmac_f32_e32 v150, v10, v10
	v_fmac_f32_e32 v151, v12, v12
	v_add_f32_e32 v152, v150, v151
	v_add_f32_e32 v160, v160, v152
	v_cvt_pk_f16_f32 v174, v10, v11
	v_cvt_pk_f16_f32 v175, v12, v13
	v_mul_f32_e32 v150, v15, v15
	v_mul_f32_e32 v151, v17, v17
	v_fmac_f32_e32 v150, v14, v14
	v_fmac_f32_e32 v151, v16, v16
	v_add_f32_e32 v152, v150, v151
	v_add_f32_e32 v160, v160, v152
	v_cvt_pk_f16_f32 v176, v14, v15
	v_cvt_pk_f16_f32 v177, v16, v17
	global_store_dwordx2 v144, v[170:171], s[10:11]
	global_store_dwordx2 v144, v[172:173], s[10:11] offset:512
	global_store_dwordx2 v144, v[174:175], s[10:11] offset:1024
	global_store_dwordx2 v144, v[176:177], s[10:11] offset:1536
	v_mul_f32_e32 v150, v19, v19
	v_mul_f32_e32 v151, v21, v21
	v_fmac_f32_e32 v150, v18, v18
	v_fmac_f32_e32 v151, v20, v20
	v_add_f32_e32 v161, v150, v151
	v_cvt_pk_f16_f32 v178, v18, v19
	v_cvt_pk_f16_f32 v179, v20, v21
	v_mul_f32_e32 v150, v23, v23
	v_mul_f32_e32 v151, v25, v25
	v_fmac_f32_e32 v150, v22, v22
	v_fmac_f32_e32 v151, v24, v24
	v_add_f32_e32 v152, v150, v151
	v_add_f32_e32 v161, v161, v152
	v_cvt_pk_f16_f32 v180, v22, v23
	v_cvt_pk_f16_f32 v181, v24, v25
	v_mul_f32_e32 v150, v27, v27
	v_mul_f32_e32 v151, v29, v29
	v_fmac_f32_e32 v150, v26, v26
	v_fmac_f32_e32 v151, v28, v28
	v_add_f32_e32 v152, v150, v151
	v_add_f32_e32 v161, v161, v152
	v_cvt_pk_f16_f32 v182, v26, v27
	v_cvt_pk_f16_f32 v183, v28, v29
	v_mul_f32_e32 v150, v31, v31
	v_mul_f32_e32 v151, v33, v33
	v_fmac_f32_e32 v150, v30, v30
	v_fmac_f32_e32 v151, v32, v32
	v_add_f32_e32 v152, v150, v151
	v_add_f32_e32 v161, v161, v152
	v_cvt_pk_f16_f32 v184, v30, v31
	v_cvt_pk_f16_f32 v185, v32, v33
	global_store_dwordx2 v145, v[178:179], s[10:11]
	global_store_dwordx2 v145, v[180:181], s[10:11] offset:512
	global_store_dwordx2 v145, v[182:183], s[10:11] offset:1024
	global_store_dwordx2 v145, v[184:185], s[10:11] offset:1536
	v_mul_f32_e32 v150, v35, v35
	v_mul_f32_e32 v151, v37, v37
	v_fmac_f32_e32 v150, v34, v34
	v_fmac_f32_e32 v151, v36, v36
	v_add_f32_e32 v162, v150, v151
	v_cvt_pk_f16_f32 v170, v34, v35
	v_cvt_pk_f16_f32 v171, v36, v37
	v_mul_f32_e32 v150, v39, v39
	v_mul_f32_e32 v151, v41, v41
	v_fmac_f32_e32 v150, v38, v38
	v_fmac_f32_e32 v151, v40, v40
	v_add_f32_e32 v152, v150, v151
	v_add_f32_e32 v162, v162, v152
	v_cvt_pk_f16_f32 v172, v38, v39
	v_cvt_pk_f16_f32 v173, v40, v41
	v_mul_f32_e32 v150, v43, v43
	v_mul_f32_e32 v151, v45, v45
	v_fmac_f32_e32 v150, v42, v42
	v_fmac_f32_e32 v151, v44, v44
	v_add_f32_e32 v152, v150, v151
	v_add_f32_e32 v162, v162, v152
	v_cvt_pk_f16_f32 v174, v42, v43
	v_cvt_pk_f16_f32 v175, v44, v45
	v_mul_f32_e32 v150, v47, v47
	v_mul_f32_e32 v151, v49, v49
	v_fmac_f32_e32 v150, v46, v46
	v_fmac_f32_e32 v151, v48, v48
	v_add_f32_e32 v152, v150, v151
	v_add_f32_e32 v162, v162, v152
; __device__ void p0_xconv(const Args& a) {
;     f16* XH = (f16*)(a.ws + WS_XH); float* SS = (float*)(a.ws + WS_SS);
;     int tid_ = threadIdx.x; asm volatile("" : "+v"(tid_));
;     const int lane = tid_ & 63, wv = tid_ >> 6;
;     const int nwv = (int)gridDim.x * 8;
;     for (int row0 = (int)blockIdx.x * 8 + wv; row0 < MROWS; row0 += 4 * nwv) {
;     ...
;                 float ss = 0.f;
; #pragma unroll
;                 for (int i = 0; i < 4; ++i) {
;                     const f32x4 x = v[r][i];
;                     ss += (x[0] * x[0] + x[1] * x[1]) + (x[2] * x[2] + x[3] * x[3]);
;                     f16x4 h; h[0] = (f16)x[0]; h[1] = (f16)x[1]; h[2] = (f16)x[2]; h[3] = (f16)x[3];
;                     *(f16x4*)(XH + (size_t)row * DM + i * 256 + lane * 4) = h;
;                 }
; #pragma unroll
;                 for (int o = 1; o < 64; o <<= 1) ss += __shfl_xor(ss, o);
;                 if (lane < 16) SS[(size_t)row * 16 + lane] = (lane == 0) ? ss : 0.f;
	v_cvt_pk_f16_f32 v176, v46, v47
	v_cvt_pk_f16_f32 v177, v48, v49
	global_store_dwordx2 v146, v[170:171], s[10:11]
	global_store_dwordx2 v146, v[172:173], s[10:11] offset:512
	global_store_dwordx2 v146, v[174:175], s[10:11] offset:1024
	global_store_dwordx2 v146, v[176:177], s[10:11] offset:1536
	v_mul_f32_e32 v150, v51, v51
	v_mul_f32_e32 v151, v53, v53
	v_fmac_f32_e32 v150, v50, v50
	v_fmac_f32_e32 v151, v52, v52
	v_add_f32_e32 v163, v150, v151
	v_cvt_pk_f16_f32 v178, v50, v51
	v_cvt_pk_f16_f32 v179, v52, v53
	v_mul_f32_e32 v150, v55, v55
	v_mul_f32_e32 v151, v57, v57
	v_fmac_f32_e32 v150, v54, v54
	v_fmac_f32_e32 v151, v56, v56
	v_add_f32_e32 v152, v150, v151
	v_add_f32_e32 v163, v163, v152
	v_cvt_pk_f16_f32 v180, v54, v55
	v_cvt_pk_f16_f32 v181, v56, v57
	v_mul_f32_e32 v150, v59, v59
	v_mul_f32_e32 v151, v61, v61
	v_fmac_f32_e32 v150, v58, v58
	v_fmac_f32_e32 v151, v60, v60
	v_add_f32_e32 v152, v150, v151
	v_add_f32_e32 v163, v163, v152
	v_cvt_pk_f16_f32 v182, v58, v59
	v_cvt_pk_f16_f32 v183, v60, v61
	v_mul_f32_e32 v150, v63, v63
	v_mul_f32_e32 v151, v65, v65
	v_fmac_f32_e32 v150, v62, v62
	v_fmac_f32_e32 v151, v64, v64
	v_add_f32_e32 v152, v150, v151
	v_add_f32_e32 v163, v163, v152
	v_cvt_pk_f16_f32 v184, v62, v63
	v_cvt_pk_f16_f32 v185, v64, v65
	global_store_dwordx2 v147, v[178:179], s[10:11]
	global_store_dwordx2 v147, v[180:181], s[10:11] offset:512
	global_store_dwordx2 v147, v[182:183], s[10:11] offset:1024
	global_store_dwordx2 v147, v[184:185], s[10:11] offset:1536
	ds_bpermute_b32 v164, v130, v160
	ds_bpermute_b32 v165, v130, v161
	ds_bpermute_b32 v166, v130, v162
	ds_bpermute_b32 v167, v130, v163
	s_waitcnt lgkmcnt(0)
	v_add_f32_e32 v160, v160, v164
	v_add_f32_e32 v161, v161, v165
	v_add_f32_e32 v162, v162, v166
	v_add_f32_e32 v163, v163, v167
	ds_bpermute_b32 v164, v131, v160
	ds_bpermute_b32 v165, v131, v161
	ds_bpermute_b32 v166, v131, v162
	ds_bpermute_b32 v167, v131, v163
	s_waitcnt lgkmcnt(0)
	v_add_f32_e32 v160, v160, v164
	v_add_f32_e32 v161, v161, v165
	v_add_f32_e32 v162, v162, v166
	v_add_f32_e32 v163, v163, v167
	ds_bpermute_b32 v164, v132, v160
	ds_bpermute_b32 v165, v132, v161
	ds_bpermute_b32 v166, v132, v162
	ds_bpermute_b32 v167, v132, v163
	s_waitcnt lgkmcnt(0)
	v_add_f32_e32 v160, v160, v164
	v_add_f32_e32 v161, v161, v165
	v_add_f32_e32 v162, v162, v166
	v_add_f32_e32 v163, v163, v167
	ds_bpermute_b32 v164, v133, v160
	ds_bpermute_b32 v165, v133, v161
	ds_bpermute_b32 v166, v133, v162
	ds_bpermute_b32 v167, v133, v163
	s_waitcnt lgkmcnt(0)
	v_add_f32_e32 v160, v160, v164
	v_add_f32_e32 v161, v161, v165
	v_add_f32_e32 v162, v162, v166
	v_add_f32_e32 v163, v163, v167
	ds_bpermute_b32 v164, v134, v160
	ds_bpermute_b32 v165, v134, v161
	ds_bpermute_b32 v166, v134, v162
	ds_bpermute_b32 v167, v134, v163
	s_waitcnt lgkmcnt(0)
	v_add_f32_e32 v160, v160, v164
	v_add_f32_e32 v161, v161, v165
	v_add_f32_e32 v162, v162, v166
	v_add_f32_e32 v163, v163, v167
	ds_bpermute_b32 v164, v135, v160
	ds_bpermute_b32 v165, v135, v161
	ds_bpermute_b32 v166, v135, v162
	ds_bpermute_b32 v167, v135, v163
	s_waitcnt lgkmcnt(0)
	v_add_f32_e32 v160, v160, v164
	v_add_f32_e32 v161, v161, v165
	v_add_f32_e32 v162, v162, v166
	v_add_f32_e32 v163, v163, v167
	v_cndmask_b32_e64 v164, 0, v160, s[12:13]
	v_cndmask_b32_e64 v165, 0, v161, s[12:13]
	v_cndmask_b32_e64 v166, 0, v162, s[12:13]
	v_cndmask_b32_e64 v167, 0, v163, s[12:13]
	s_mov_b64 exec, 0xffff
	global_store_dword v186, v164, s[6:7]
	global_store_dword v187, v165, s[6:7]
	global_store_dword v188, v166, s[6:7]
	global_store_dword v189, v167, s[6:7]
	s_mov_b64 exec, -1
	s_barrier
	s_branch .LBB0_112
.LBB0_91:
	v_mov_b32_e32 v1, v0
	s_barrier
	s_mov_b32 s3, 0xc000
	v_ashrrev_i32_e32 v2, 6, v1
	v_lshl_add_u32 v78, s2, 3, v2
	v_add_u32_e32 v78, 0x9000, v78
	v_cmp_gt_i32_e32 vcc, s3, v78
	s_and_saveexec_b64 s[20:21], vcc
	s_cbranch_execz .LBB0_111
	v_and_b32_e32 v1, 63, v1
	v_mov_b32_e32 v67, 0
	v_lshlrev_b32_e32 v66, 2, v1
	v_lshlrev_b32_e32 v2, 3, v1
	v_mov_b32_e32 v3, v67
	s_load_dword s36, s[4:5], 0x0
	v_lshl_add_u64 v[68:69], s[40:41], 0, v[2:3]
	v_lshl_add_u64 v[2:3], s[40:41], 0, v[66:67]
	s_mov_b64 s[4:5], 0x1f800000
	v_cmp_gt_u32_e32 vcc, 16, v1
	v_lshl_add_u64 v[70:71], v[2:3], 0, s[4:5]
	v_cmp_eq_u32_e64 s[4:5], 0, v1
	v_mbcnt_lo_u32_b32 v1, -1, 0
	v_mbcnt_hi_u32_b32 v2, -1, v1
	v_and_b32_e32 v1, 64, v2
	v_add_u32_e32 v3, 64, v1
	v_xor_b32_e32 v1, 1, v2
	v_cmp_lt_i32_e64 s[6:7], v1, v3
	v_xor_b32_e32 v4, 2, v2
	s_waitcnt lgkmcnt(0)
	s_lshl_b32 s9, s36, 3
	v_cndmask_b32_e64 v1, v2, v1, s[6:7]
	v_cmp_lt_i32_e64 s[6:7], v4, v3
	s_add_i32 s44, s9, s9
	v_lshlrev_b32_e32 v1, 2, v1
	v_cndmask_b32_e64 v4, v2, v4, s[6:7]
	v_lshlrev_b32_e32 v80, 2, v4
	v_xor_b32_e32 v4, 4, v2
	v_cmp_lt_i32_e64 s[6:7], v4, v3
	s_lshl_b32 s33, s36, 4
	s_mul_i32 s36, s36, 24
	v_cndmask_b32_e64 v4, v2, v4, s[6:7]
	v_lshlrev_b32_e32 v81, 2, v4
	v_xor_b32_e32 v4, 8, v2
	v_cmp_lt_i32_e64 s[6:7], v4, v3
	s_mov_b64 s[22:23], 0
	s_movk_i32 s37, 0x4000
	v_cndmask_b32_e64 v4, v2, v4, s[6:7]
	v_lshlrev_b32_e32 v82, 2, v4
	v_xor_b32_e32 v4, 16, v2
	v_cmp_lt_i32_e64 s[6:7], v4, v3
	v_mov_b32_e32 v85, s19
	v_mov_b32_e32 v86, s17
	v_cndmask_b32_e64 v4, v2, v4, s[6:7]
	v_lshlrev_b32_e32 v83, 2, v4
	v_xor_b32_e32 v4, 32, v2
	v_cmp_lt_i32_e64 s[6:7], v4, v3
	v_mov_b32_e32 v87, s18
	v_mov_b32_e32 v88, s16
	v_cndmask_b32_e64 v2, v2, v4, s[6:7]
	v_lshlrev_b32_e32 v84, 2, v2
	v_lshlrev_b32_e32 v66, 2, v66
	s_add_i32 s44, s44, s9
	s_mov_b32 s45, 0xbfff
	s_branch .LBB0_94
